# SSD prompt chunk loop: batched LDS reads ahead of MFMAs + prefetch loads spread over chunk
# speedup vs baseline: 1.0063x; 1.0063x over previous
.LBB0_1188:
	v_add_u32_e32 v92, s80, v167
	s_movk_i32 s68, 0xc00
	v_cvt_pk_bf16_f32 v76, v76, v77
	v_cvt_pk_bf16_f32 v77, v78, v79
	v_mad_i64_i32 v[78:79], s[68:69], v92, s68, v[158:159]
	global_store_dwordx2 v[78:79], v[76:77], off
	v_cvt_pk_bf16_f32 v76, v80, v81
	v_cvt_pk_bf16_f32 v77, v82, v83
	global_store_dwordx2 v[78:79], v[76:77], off offset:32
	v_cvt_pk_bf16_f32 v76, v84, v85
	v_cvt_pk_bf16_f32 v77, v86, v87
	global_store_dwordx2 v[78:79], v[76:77], off offset:64
	v_cvt_pk_bf16_f32 v76, v88, v89
	v_cvt_pk_bf16_f32 v77, v90, v91
	global_store_dwordx2 v[78:79], v[76:77], off offset:96
	v_mul_f32_e32 v76, 0x3fb8aa3b, v236
	v_exp_f32_e32 v76, v76
	s_cmpk_eq_i32 s80, 0x780
	s_cbranch_scc1 .Lssd_pf_g4
	global_load_dwordx4 v[44:47], v[44:45], off offset:1024
	s_nop 0
	global_load_dwordx4 v[48:51], v[48:49], off
	s_nop 0
	global_load_dwordx4 v[52:55], v[52:53], off
	s_nop 0
	global_load_dwordx4 v[56:59], v[56:57], off
.Lssd_pf_g4:
	s_add_i32 s74, s74, 1
	s_addk_i32 s80, 0x80
	s_cmpk_lg_i32 s80, 0x800
	v_pk_mul_f32 v[62:63], v[62:63], v[76:77] op_sel_hi:[1,0]
	v_pk_mul_f32 v[60:61], v[60:61], v[76:77] op_sel_hi:[1,0]
	v_pk_mul_f32 v[66:67], v[66:67], v[76:77] op_sel_hi:[1,0]
	v_pk_mul_f32 v[64:65], v[64:65], v[76:77] op_sel_hi:[1,0]
	v_pk_mul_f32 v[70:71], v[70:71], v[76:77] op_sel_hi:[1,0]
	v_pk_mul_f32 v[68:69], v[68:69], v[76:77] op_sel_hi:[1,0]
	v_pk_mul_f32 v[74:75], v[74:75], v[76:77] op_sel_hi:[1,0]
	v_pk_mul_f32 v[72:73], v[72:73], v[76:77] op_sel_hi:[1,0]
	v_add_u32_e32 v136, v211, v207
	v_add_u32_e32 v137, v211, v209
	v_add_u32_e32 v138, v211, v210
	ds_read_b128 v[76:79], v230
	ds_read_b128 v[80:83], v231
	ds_read_b128 v[84:87], v231 offset:4352
	ds_read_b128 v[88:91], v231 offset:8704
	ds_read_b128 v[92:95], v231 offset:13056
	ds_read_b128 v[96:99], v230 offset:64
	ds_read_b128 v[100:103], v136
	ds_read_b128 v[104:107], v232 offset:4352
	ds_read_b128 v[108:111], v232 offset:8704
	ds_read_b128 v[112:115], v232 offset:13056
	ds_read_b128 v[116:119], v230 offset:128
	ds_read_b128 v[120:123], v137
	ds_read_b128 v[124:127], v233 offset:4352
	ds_read_b128 v[128:131], v233 offset:8704
	ds_read_b128 v[132:135], v233 offset:13056
	s_waitcnt lgkmcnt(13)
	v_mfma_f32_16x16x32_bf16 v[60:63], v[76:79], v[80:83], v[60:63]
	s_waitcnt lgkmcnt(12)
	v_mfma_f32_16x16x32_bf16 v[64:67], v[76:79], v[84:87], v[64:67]
	s_waitcnt lgkmcnt(11)
	v_mfma_f32_16x16x32_bf16 v[68:71], v[76:79], v[88:91], v[68:71]
	s_waitcnt lgkmcnt(10)
	v_mfma_f32_16x16x32_bf16 v[72:75], v[76:79], v[92:95], v[72:75]
	ds_read_b128 v[76:79], v230 offset:192
	ds_read_b128 v[80:83], v138
	ds_read_b128 v[84:87], v234 offset:4352
	ds_read_b128 v[88:91], v234 offset:8704
	ds_read_b128 v[92:95], v234 offset:13056
	s_waitcnt lgkmcnt(13)
	v_mfma_f32_16x16x32_bf16 v[60:63], v[96:99], v[100:103], v[60:63]
	s_waitcnt lgkmcnt(12)
	v_mfma_f32_16x16x32_bf16 v[64:67], v[96:99], v[104:107], v[64:67]
	s_waitcnt lgkmcnt(11)
	v_mfma_f32_16x16x32_bf16 v[68:71], v[96:99], v[108:111], v[68:71]
	s_waitcnt lgkmcnt(10)
	v_mfma_f32_16x16x32_bf16 v[72:75], v[96:99], v[112:115], v[72:75]
	s_waitcnt lgkmcnt(8)
	v_mfma_f32_16x16x32_bf16 v[60:63], v[116:119], v[120:123], v[60:63]
	s_waitcnt lgkmcnt(7)
	v_mfma_f32_16x16x32_bf16 v[64:67], v[116:119], v[124:127], v[64:67]
	s_waitcnt lgkmcnt(6)
	v_mfma_f32_16x16x32_bf16 v[68:71], v[116:119], v[128:131], v[68:71]
	s_waitcnt lgkmcnt(5)
	v_mfma_f32_16x16x32_bf16 v[72:75], v[116:119], v[132:135], v[72:75]
	s_waitcnt lgkmcnt(3)
	v_mfma_f32_16x16x32_bf16 v[60:63], v[76:79], v[80:83], v[60:63]
	s_waitcnt lgkmcnt(2)
	v_mfma_f32_16x16x32_bf16 v[64:67], v[76:79], v[84:87], v[64:67]
	s_waitcnt lgkmcnt(1)
	v_mfma_f32_16x16x32_bf16 v[68:71], v[76:79], v[88:91], v[68:71]
	s_waitcnt lgkmcnt(0)
	v_mfma_f32_16x16x32_bf16 v[72:75], v[76:79], v[92:95], v[72:75]
	s_nop 3
	v_cvt_pk_bf16_f32 v76, v60, v61
	v_cvt_pk_bf16_f32 v77, v62, v63
	ds_write_b64 v235, v[76:77]
	v_cvt_pk_bf16_f32 v76, v64, v65
	v_cvt_pk_bf16_f32 v77, v66, v67
	ds_write_b64 v235, v[76:77] offset:4352
	v_cvt_pk_bf16_f32 v76, v68, v69
	v_cvt_pk_bf16_f32 v77, v70, v71
	ds_write_b64 v235, v[76:77] offset:8704
	v_cvt_pk_bf16_f32 v76, v72, v73
	v_cvt_pk_bf16_f32 v77, v74, v75
	ds_write_b64 v235, v[76:77] offset:13056
	s_waitcnt lgkmcnt(0)
	s_barrier
	s_cbranch_scc0 .LBB0_1067

.LBB0_1193:
	v_add_u32_e32 v237, v181, v179
	ds_read_b32 v238, v218
	ds_read_b128 v[132:135], v237
	ds_read_b128 v[128:131], v237 offset:64
	ds_read_b128 v[120:123], v237 offset:128
	ds_read_b128 v[116:119], v237 offset:192
	ds_read_b128 v[92:95], v217
	ds_read_b128 v[96:99], v217 offset:64
	ds_read_b128 v[100:103], v217 offset:128
	ds_read_b128 v[104:107], v217 offset:192
	ds_read_b128 v[108:111], v217 offset:4352
	ds_read_b128 v[112:115], v217 offset:4416
	ds_read_b128 v[124:127], v217 offset:4480
	ds_read_b128 v[136:139], v217 offset:4544
	v_add_u32_e32 v141, v182, v194
	s_waitcnt lgkmcnt(7)
	v_mfma_f32_16x16x32_bf16 v[76:79], v[92:95], v[132:135], 0
	s_waitcnt lgkmcnt(6)
	v_mfma_f32_16x16x32_bf16 v[76:79], v[96:99], v[128:131], v[76:79]
	s_waitcnt lgkmcnt(5)
	v_mfma_f32_16x16x32_bf16 v[76:79], v[100:103], v[120:123], v[76:79]
	s_waitcnt lgkmcnt(4)
	v_mfma_f32_16x16x32_bf16 v[76:79], v[104:107], v[116:119], v[76:79]
	ds_read_b128 v[92:95], v217 offset:8704
	ds_read_b128 v[96:99], v217 offset:8768
	ds_read_b128 v[100:103], v217 offset:8832
	ds_read_b128 v[104:107], v217 offset:8896
	s_waitcnt lgkmcnt(7)
	v_mfma_f32_16x16x32_bf16 v[80:83], v[108:111], v[132:135], 0
	s_waitcnt lgkmcnt(6)
	v_mfma_f32_16x16x32_bf16 v[80:83], v[112:115], v[128:131], v[80:83]
	s_waitcnt lgkmcnt(5)
	v_mfma_f32_16x16x32_bf16 v[80:83], v[124:127], v[120:123], v[80:83]
	s_waitcnt lgkmcnt(4)
	v_mfma_f32_16x16x32_bf16 v[80:83], v[136:139], v[116:119], v[80:83]
	ds_read_b128 v[108:111], v217 offset:13056
	ds_read_b128 v[112:115], v217 offset:13120
	ds_read_b128 v[124:127], v217 offset:13184
	ds_read_b128 v[136:139], v217 offset:13248
	s_waitcnt lgkmcnt(7)
	v_mfma_f32_16x16x32_bf16 v[84:87], v[92:95], v[132:135], 0
	s_waitcnt lgkmcnt(6)
	v_mfma_f32_16x16x32_bf16 v[84:87], v[96:99], v[128:131], v[84:87]
	s_waitcnt lgkmcnt(5)
	v_mfma_f32_16x16x32_bf16 v[84:87], v[100:103], v[120:123], v[84:87]
	s_waitcnt lgkmcnt(4)
	v_mfma_f32_16x16x32_bf16 v[84:87], v[104:107], v[116:119], v[84:87]
	ds_read_b128 v[92:95], v141 offset:34816
	ds_read_b128 v[96:99], v141 offset:34880
	ds_read_b128 v[100:103], v141 offset:34944
	ds_read_b128 v[104:107], v141 offset:35008
	s_waitcnt lgkmcnt(7)
	v_mfma_f32_16x16x32_bf16 v[88:91], v[108:111], v[132:135], 0
	s_waitcnt lgkmcnt(6)
	v_mfma_f32_16x16x32_bf16 v[88:91], v[112:115], v[128:131], v[88:91]
	s_waitcnt lgkmcnt(5)
	v_mfma_f32_16x16x32_bf16 v[88:91], v[124:127], v[120:123], v[88:91]
	s_waitcnt lgkmcnt(4)
	v_mfma_f32_16x16x32_bf16 v[88:91], v[136:139], v[116:119], v[88:91]
	s_cmpk_eq_i32 s80, 0x780
	s_cbranch_scc1 .Lssd_pf_g2
	global_load_dwordx4 v[12:15], v[12:13], off
	s_nop 0
	global_load_dwordx4 v[16:19], v[20:21], off
	s_nop 0
	global_load_dwordx4 v[20:23], v[20:21], off offset:1024
	s_nop 0
	global_load_dwordx4 v[24:27], v[24:25], off
.Lssd_pf_g2:
	v_mov_b32_e32 v136, 0
	v_mov_b32_e32 v137, 0
	v_mov_b32_e32 v138, 0
	v_mov_b32_e32 v139, 0
	s_andn2_b64 vcc, exec, s[88:89]
	s_cbranch_vccnz .LBB0_1195
	s_waitcnt lgkmcnt(3)
	v_mfma_f32_16x16x32_bf16 v[136:139], v[92:95], v[132:135], 0
	s_waitcnt lgkmcnt(2)
	v_mfma_f32_16x16x32_bf16 v[136:139], v[96:99], v[128:131], v[136:139]
	s_waitcnt lgkmcnt(1)
	v_mfma_f32_16x16x32_bf16 v[136:139], v[100:103], v[120:123], v[136:139]
	s_waitcnt lgkmcnt(0)
	v_mfma_f32_16x16x32_bf16 v[136:139], v[104:107], v[116:119], v[136:139]
.LBB0_1195:
	s_andn2_b64 vcc, exec, s[38:39]
	v_mov_b32_e32 v124, 0
	v_mov_b32_e32 v125, 0
	v_mov_b32_e32 v126, 0
	v_mov_b32_e32 v127, 0
	s_cbranch_vccnz .LBB0_1197
	ds_read_b128 v[92:95], v141 offset:39168
	ds_read_b128 v[96:99], v141 offset:39232
	ds_read_b128 v[100:103], v141 offset:39296
	ds_read_b128 v[104:107], v141 offset:39360
	s_waitcnt lgkmcnt(3)
	v_mfma_f32_16x16x32_bf16 v[124:127], v[92:95], v[132:135], 0
	s_waitcnt lgkmcnt(2)
	v_mfma_f32_16x16x32_bf16 v[124:127], v[96:99], v[128:131], v[124:127]
	s_waitcnt lgkmcnt(1)
	v_mfma_f32_16x16x32_bf16 v[124:127], v[100:103], v[120:123], v[124:127]
	s_waitcnt lgkmcnt(0)
	v_mfma_f32_16x16x32_bf16 v[124:127], v[104:107], v[116:119], v[124:127]
.LBB0_1197:
	s_andn2_b64 vcc, exec, s[40:41]
	v_mov_b32_e32 v112, 0
	v_mov_b32_e32 v113, 0
	v_mov_b32_e32 v114, 0
	v_mov_b32_e32 v115, 0
	s_cbranch_vccnz .LBB0_1199
	ds_read_b128 v[92:95], v141 offset:43520
	ds_read_b128 v[96:99], v141 offset:43584
	ds_read_b128 v[100:103], v141 offset:43648
	ds_read_b128 v[104:107], v141 offset:43712
	s_waitcnt lgkmcnt(3)
	v_mfma_f32_16x16x32_bf16 v[112:115], v[92:95], v[132:135], 0
	s_waitcnt lgkmcnt(2)
	v_mfma_f32_16x16x32_bf16 v[112:115], v[96:99], v[128:131], v[112:115]
	s_waitcnt lgkmcnt(1)
	v_mfma_f32_16x16x32_bf16 v[112:115], v[100:103], v[120:123], v[112:115]
	s_waitcnt lgkmcnt(0)
	v_mfma_f32_16x16x32_bf16 v[112:115], v[104:107], v[116:119], v[112:115]
.LBB0_1199:
	s_andn2_b64 vcc, exec, s[42:43]
	v_mov_b32_e32 v108, 0
	v_mov_b32_e32 v109, 0
	v_mov_b32_e32 v110, 0
	v_mov_b32_e32 v111, 0
	s_cbranch_vccnz .LBB0_1201
	ds_read_b128 v[92:95], v141 offset:47872
	ds_read_b128 v[96:99], v141 offset:47936
	ds_read_b128 v[100:103], v141 offset:48000
	ds_read_b128 v[104:107], v141 offset:48064
	s_waitcnt lgkmcnt(3)
	v_mfma_f32_16x16x32_bf16 v[108:111], v[92:95], v[132:135], 0
	s_waitcnt lgkmcnt(2)
	v_mfma_f32_16x16x32_bf16 v[108:111], v[96:99], v[128:131], v[108:111]
	s_waitcnt lgkmcnt(1)
	v_mfma_f32_16x16x32_bf16 v[108:111], v[100:103], v[120:123], v[108:111]
	s_waitcnt lgkmcnt(0)
	v_mfma_f32_16x16x32_bf16 v[108:111], v[104:107], v[116:119], v[108:111]
.LBB0_1201:
	s_andn2_b64 vcc, exec, s[44:45]
	v_mov_b32_e32 v104, 0
	v_mov_b32_e32 v105, 0
	v_mov_b32_e32 v106, 0
	v_mov_b32_e32 v107, 0
	s_cbranch_vccnz .LBB0_1203
	ds_read_b128 v[92:95], v141 offset:52224
	ds_read_b128 v[96:99], v141 offset:52288
	ds_read_b128 v[100:103], v141 offset:52352
	ds_read_b128 v[240:243], v141 offset:52416
	s_waitcnt lgkmcnt(3)
	v_mfma_f32_16x16x32_bf16 v[104:107], v[92:95], v[132:135], 0
	s_waitcnt lgkmcnt(2)
	v_mfma_f32_16x16x32_bf16 v[104:107], v[96:99], v[128:131], v[104:107]
	s_waitcnt lgkmcnt(1)
	v_mfma_f32_16x16x32_bf16 v[104:107], v[100:103], v[120:123], v[104:107]
	s_waitcnt lgkmcnt(0)
	v_mfma_f32_16x16x32_bf16 v[104:107], v[240:243], v[116:119], v[104:107]
.LBB0_1203:
	s_andn2_b64 vcc, exec, s[46:47]
	v_mov_b32_e32 v100, 0
	v_mov_b32_e32 v101, 0
	v_mov_b32_e32 v102, 0
	v_mov_b32_e32 v103, 0
	s_cbranch_vccnz .LBB0_1205
	ds_read_b128 v[92:95], v141 offset:56576
	ds_read_b128 v[96:99], v141 offset:56640
	ds_read_b128 v[240:243], v141 offset:56704
	ds_read_b128 v[244:247], v141 offset:56768
	s_waitcnt lgkmcnt(3)
	v_mfma_f32_16x16x32_bf16 v[100:103], v[92:95], v[132:135], 0
	s_waitcnt lgkmcnt(2)
	v_mfma_f32_16x16x32_bf16 v[100:103], v[96:99], v[128:131], v[100:103]
	s_waitcnt lgkmcnt(1)
	v_mfma_f32_16x16x32_bf16 v[100:103], v[240:243], v[120:123], v[100:103]
	s_waitcnt lgkmcnt(0)
	v_mfma_f32_16x16x32_bf16 v[100:103], v[244:247], v[116:119], v[100:103]
.LBB0_1205:
	s_andn2_b64 vcc, exec, s[48:49]
	v_mov_b32_e32 v96, 0
	v_mov_b32_e32 v97, 0
	v_mov_b32_e32 v98, 0
	v_mov_b32_e32 v99, 0
	s_cbranch_vccnz .LBB0_1207
	ds_read_b128 v[92:95], v141 offset:60928
	ds_read_b128 v[240:243], v141 offset:60992
	ds_read_b128 v[244:247], v141 offset:61056
	s_waitcnt lgkmcnt(2)
	v_mfma_f32_16x16x32_bf16 v[96:99], v[92:95], v[132:135], 0
	ds_read_b128 v[92:95], v141 offset:61120
	s_waitcnt lgkmcnt(2)
	v_mfma_f32_16x16x32_bf16 v[96:99], v[240:243], v[128:131], v[96:99]
	s_waitcnt lgkmcnt(1)
	v_mfma_f32_16x16x32_bf16 v[96:99], v[244:247], v[120:123], v[96:99]
	s_waitcnt lgkmcnt(0)
	v_mfma_f32_16x16x32_bf16 v[96:99], v[92:95], v[116:119], v[96:99]
.LBB0_1207:
	s_nop 1
	v_mov_b32_e32 v92, 0
	s_andn2_b64 vcc, exec, s[50:51]
	v_mov_b32_e32 v93, v92
	v_mov_b32_e32 v94, v92
	v_mov_b32_e32 v95, v92
	s_cbranch_vccnz .LBB0_1209
	ds_read_b128 v[240:243], v141 offset:65280
	ds_read_b128 v[244:247], v141 offset:65344
	s_waitcnt lgkmcnt(1)
	v_mfma_f32_16x16x32_bf16 v[92:95], v[240:243], v[132:135], 0
	ds_read_b128 v[240:243], v141 offset:65408
	s_waitcnt lgkmcnt(1)
	v_mfma_f32_16x16x32_bf16 v[92:95], v[244:247], v[128:131], v[92:95]
	ds_read_b128 v[244:247], v141 offset:65472
	s_waitcnt lgkmcnt(1)
	v_mfma_f32_16x16x32_bf16 v[92:95], v[240:243], v[120:123], v[92:95]
	s_waitcnt lgkmcnt(0)
	v_mfma_f32_16x16x32_bf16 v[92:95], v[244:247], v[116:119], v[92:95]
.LBB0_1209:
	s_waitcnt lgkmcnt(0)
	s_barrier
	s_cmpk_eq_i32 s80, 0x780
	s_cbranch_scc1 .Lssd_pf_g3
	global_load_dwordx4 v[32:35], v[28:29], off
	s_nop 0
	global_load_dwordx4 v[28:31], v[28:29], off offset:1024
	s_nop 0
	global_load_dwordx4 v[36:39], v[36:37], off
	s_nop 0
	global_load_dwordx4 v[40:43], v[44:45], off
.Lssd_pf_g3:
	v_cndmask_b32_e64 v116, 0, 1, s[52:53]
	v_cmp_ne_u32_e64 s[90:91], 1, v116
	s_andn2_b64 vcc, exec, s[52:53]
	s_cbranch_vccnz .LBB0_1221
	s_mov_b64 s[76:77], -1
	s_and_b64 vcc, exec, s[54:55]
	s_cbranch_vccz .LBB0_1212
	v_add_u32_e32 v116, 0x26400, v182
	ds_read_b128 v[116:119], v116
	v_add_u32_e32 v120, 0x26600, v182
	ds_read_b128 v[120:123], v120
	s_mov_b64 s[76:77], 0
	s_waitcnt lgkmcnt(1)
	v_sub_f32_e32 v116, v238, v116
	v_sub_f32_e32 v117, v238, v117
	v_mul_f32_e32 v116, 0x3fb8aa3b, v116
	v_mul_f32_e32 v117, 0x3fb8aa3b, v117
	v_exp_f32_e32 v116, v116
	v_sub_f32_e32 v118, v238, v118
	v_sub_f32_e32 v119, v238, v119
	v_exp_f32_e32 v117, v117
	v_mul_f32_e32 v118, 0x3fb8aa3b, v118
	v_mul_f32_e32 v119, 0x3fb8aa3b, v119
	v_exp_f32_e32 v118, v118
	v_exp_f32_e32 v119, v119
	v_mul_f32_e32 v116, v136, v116
	v_mul_f32_e32 v117, v137, v117
	s_waitcnt lgkmcnt(0)
	v_mul_f32_e32 v116, v120, v116
	v_mul_f32_e32 v117, v121, v117
	v_cndmask_b32_e64 v116, v116, 0, s[20:21]
	v_pk_mul_f32 v[118:119], v[138:139], v[118:119]
	v_add_f32_e32 v120, v140, v116
	v_cndmask_b32_e64 v117, 0, v117, s[24:25]
	v_pk_mul_f32 v[118:119], v[122:123], v[118:119]
	v_cndmask_b32_e64 v116, v116, v120, s[22:23]
	v_add_f32_e32 v120, v140, v117
	v_cndmask_b32_e64 v119, v119, 0, s[28:29]
	v_cndmask_b32_e64 v118, v118, 0, s[30:31]
	v_cndmask_b32_e64 v117, v117, v120, s[26:27]
	v_pk_add_f32 v[120:121], v[160:161], v[118:119]
	s_nop 0
	v_cndmask_b32_e64 v118, v118, v120, s[36:37]
	v_cndmask_b32_e64 v119, v119, v121, s[34:35]

.LBB0_1263:
	v_mul_f32_e32 v92, 0x3fb8aa3b, v238
	v_exp_f32_e32 v92, v92
	s_waitcnt lgkmcnt(0)
	s_and_b64 vcc, exec, s[90:91]
	v_pk_mul_f32 v[78:79], v[78:79], v[92:93] op_sel_hi:[1,0]
	v_pk_mul_f32 v[76:77], v[76:77], v[92:93] op_sel_hi:[1,0]
	v_pk_mul_f32 v[82:83], v[82:83], v[92:93] op_sel_hi:[1,0]
	v_pk_mul_f32 v[80:81], v[80:81], v[92:93] op_sel_hi:[1,0]
	v_pk_mul_f32 v[86:87], v[86:87], v[92:93] op_sel_hi:[1,0]
	v_pk_mul_f32 v[84:85], v[84:85], v[92:93] op_sel_hi:[1,0]
	v_pk_mul_f32 v[90:91], v[90:91], v[92:93] op_sel_hi:[1,0]
	v_pk_mul_f32 v[88:89], v[88:89], v[92:93] op_sel_hi:[1,0]
	s_cbranch_vccnz .LBB0_1267
	ds_read_b128 v[92:95], v237 offset:34816
	ds_read_b128 v[96:99], v226
	ds_read_b128 v[100:103], v226 offset:4352
	ds_read_b128 v[104:107], v226 offset:8704
	ds_read_b128 v[108:111], v226 offset:13056
	s_waitcnt lgkmcnt(3)
	v_mfma_f32_16x16x32_bf16 v[76:79], v[96:99], v[92:95], v[76:79]
	s_waitcnt lgkmcnt(2)
	v_mfma_f32_16x16x32_bf16 v[80:83], v[100:103], v[92:95], v[80:83]
	s_waitcnt lgkmcnt(1)
	v_mfma_f32_16x16x32_bf16 v[84:87], v[104:107], v[92:95], v[84:87]
	s_waitcnt lgkmcnt(0)
	v_mfma_f32_16x16x32_bf16 v[88:91], v[108:111], v[92:95], v[88:91]
	s_and_b64 vcc, exec, s[92:93]
	s_cbranch_vccz .LBB0_1268

.LBB0_1266:
	v_add_u32_e32 v96, v208, v209
	ds_read_b128 v[92:95], v237 offset:34944
	ds_read_b128 v[96:99], v96
	ds_read_b128 v[100:103], v228 offset:4352
	ds_read_b128 v[104:107], v228 offset:8704
	ds_read_b128 v[108:111], v228 offset:13056
	s_waitcnt lgkmcnt(3)
	v_mfma_f32_16x16x32_bf16 v[76:79], v[96:99], v[92:95], v[76:79]
	s_waitcnt lgkmcnt(2)
	v_mfma_f32_16x16x32_bf16 v[80:83], v[100:103], v[92:95], v[80:83]
	s_waitcnt lgkmcnt(1)
	v_mfma_f32_16x16x32_bf16 v[84:87], v[104:107], v[92:95], v[84:87]
	s_waitcnt lgkmcnt(0)
	v_mfma_f32_16x16x32_bf16 v[88:91], v[108:111], v[92:95], v[88:91]
	s_and_b64 vcc, exec, s[78:79]
	s_cbranch_vccnz .LBB0_1188
	s_branch .LBB0_1270

.LBB0_1268:
	v_add_u32_e32 v96, v208, v207
	ds_read_b128 v[92:95], v237 offset:34880
	ds_read_b128 v[96:99], v96
	ds_read_b128 v[100:103], v227 offset:4352
	ds_read_b128 v[104:107], v227 offset:8704
	ds_read_b128 v[108:111], v227 offset:13056
	s_waitcnt lgkmcnt(3)
	v_mfma_f32_16x16x32_bf16 v[76:79], v[96:99], v[92:95], v[76:79]
	s_waitcnt lgkmcnt(2)
	v_mfma_f32_16x16x32_bf16 v[80:83], v[100:103], v[92:95], v[80:83]
	s_waitcnt lgkmcnt(1)
	v_mfma_f32_16x16x32_bf16 v[84:87], v[104:107], v[92:95], v[84:87]
	s_waitcnt lgkmcnt(0)
	v_mfma_f32_16x16x32_bf16 v[88:91], v[108:111], v[92:95], v[88:91]
	s_and_b64 vcc, exec, s[76:77]
	s_cbranch_vccz .LBB0_1266

.LBB0_1270:
	v_add_u32_e32 v96, v208, v210
	ds_read_b128 v[92:95], v237 offset:35008
	ds_read_b128 v[96:99], v96
	ds_read_b128 v[100:103], v229 offset:4352
	ds_read_b128 v[104:107], v229 offset:8704
	ds_read_b128 v[108:111], v229 offset:13056
	s_waitcnt lgkmcnt(3)
	v_mfma_f32_16x16x32_bf16 v[76:79], v[96:99], v[92:95], v[76:79]
	s_waitcnt lgkmcnt(2)
	v_mfma_f32_16x16x32_bf16 v[80:83], v[100:103], v[92:95], v[80:83]
	s_waitcnt lgkmcnt(1)
	v_mfma_f32_16x16x32_bf16 v[84:87], v[104:107], v[92:95], v[84:87]
	s_waitcnt lgkmcnt(0)
	v_mfma_f32_16x16x32_bf16 v[88:91], v[108:111], v[92:95], v[88:91]
	s_branch .LBB0_1188
